# LayerNorm phases: gamma/beta chunks loaded once per phase; per-chunk reload + vmcnt(0) (store-ack serialisation) removed
# speedup vs baseline: 1.0186x; 1.0021x over previous
; __device__ __forceinline__ void ln_finish_row(int r, int lane, f32x4 (&x)[8], float* dstf, bf16_t* dstb, const float* g, const float* bta) {
;     ...
;   for (int k = 0; k < 8; ++k) {
;     const int col = 256 * k + 4 * lane;
;     const f32x4 gg = *(const f32x4*)(g + col), bb = *(const f32x4*)(bta + col);
; __device__ __forceinline__ void phase_ln(const Params& p, const float* src, float* dstf, bf16_t* dstb, const float* g, const float* bta, int which) {
;   int tid = threadIdx.x; asm volatile("" : "+v"(tid));
;   const int w = tid >> 6, lane = tid & 63;
;   const int nw = gridDim.x * 8;
;   for (int r = blockIdx.x * 8 + w; r < NTOK; r += 2 * nw) {
;     const int r2 = r + nw;
.LBB0_88:
	s_and_b64 vcc, exec, s[36:37]
	s_cbranch_vccz .LBB0_161
	v_mov_b32_e32 v0, v226
	v_readlane_b32 s29, v252, 44
	v_ashrrev_i32_e32 v1, 6, v0
	s_nop 0
	v_add_u32_e32 v66, s29, v1
	s_movk_i32 s29, 0x2400
	v_cmp_gt_i32_e32 vcc, s29, v66
	s_and_saveexec_b64 s[44:45], vcc
	s_cbranch_execz .LBB0_160
	v_lshlrev_b32_e32 v2, 2, v0
	v_and_b32_e32 v68, 0xfc, v2
	v_and_b32_e32 v2, 64, v230
	v_add_u32_e32 v2, 64, v2
	v_xor_b32_e32 v3, 32, v230
	v_cmp_lt_i32_e32 vcc, v3, v2
	v_readlane_b32 s48, v251, 16
	v_readlane_b32 s52, v251, 20
	v_cndmask_b32_e32 v3, v230, v3, vcc
	v_lshlrev_b32_e32 v69, 2, v3
	v_xor_b32_e32 v3, 16, v230
	v_cmp_lt_i32_e32 vcc, v3, v2
	v_readlane_b32 s53, v251, 21
	v_readlane_b32 s54, v251, 22
	v_cndmask_b32_e32 v3, v230, v3, vcc
	v_lshlrev_b32_e32 v124, 2, v3
	v_xor_b32_e32 v3, 8, v230
	v_cmp_lt_i32_e32 vcc, v3, v2
	v_readlane_b32 s55, v251, 23
	v_mov_b32_e32 v5, v65
	v_cndmask_b32_e32 v3, v230, v3, vcc
	v_lshlrev_b32_e32 v125, 2, v3
	v_xor_b32_e32 v3, 4, v230
	v_cmp_lt_i32_e32 vcc, v3, v2
	v_mov_b32_e32 v7, v65
	v_readlane_b32 s34, v254, 30
	v_cndmask_b32_e32 v3, v230, v3, vcc
	v_lshlrev_b32_e32 v126, 2, v3
	v_xor_b32_e32 v3, 2, v230
	v_cmp_lt_i32_e32 vcc, v3, v2
	v_lshlrev_b32_e32 v64, 2, v68
	v_readlane_b32 s35, v254, 31
	v_cndmask_b32_e32 v3, v230, v3, vcc
	v_lshlrev_b32_e32 v127, 2, v3
	v_xor_b32_e32 v3, 1, v230
	v_cmp_lt_i32_e32 vcc, v3, v2
	v_mov_b32_e32 v9, v65
	v_lshl_add_u64 v[70:71], s[34:35], 0, v[64:65]
	v_cndmask_b32_e32 v2, v230, v3, vcc
	v_lshlrev_b32_e32 v128, 2, v2
	v_or_b32_e32 v2, 0x400, v68
	v_lshlrev_b32_e32 v4, 2, v2
	v_lshl_add_u64 v[76:77], s[52:53], 0, v[4:5]
	v_lshl_add_u64 v[78:79], s[54:55], 0, v[4:5]
	v_or_b32_e32 v4, 0x500, v68
	v_lshlrev_b32_e32 v6, 2, v4
	v_lshl_add_u64 v[80:81], s[52:53], 0, v[6:7]
	v_lshl_add_u64 v[82:83], s[54:55], 0, v[6:7]
	v_or_b32_e32 v6, 0x600, v68
	v_lshlrev_b32_e32 v8, 2, v6
	v_lshl_add_u64 v[84:85], s[52:53], 0, v[8:9]
	v_lshl_add_u64 v[86:87], s[54:55], 0, v[8:9]
	v_or_b32_e32 v8, 0x700, v68
	v_readlane_b32 s34, v253, 60
	v_ashrrev_i32_e32 v67, 31, v66
	v_lshl_add_u64 v[72:73], s[52:53], 0, v[64:65]
	v_lshl_add_u64 v[74:75], s[54:55], 0, v[64:65]
	v_lshlrev_b32_e32 v10, 2, v8
	v_mov_b32_e32 v11, v65
	v_lshl_add_u64 v[92:93], s[38:39], 0, v[64:65]
	v_lshlrev_b32_e32 v64, 1, v68
	v_readlane_b32 s35, v253, 61
	v_readlane_b32 s29, v255, 8
	v_lshlrev_b64 v[96:97], 12, v[66:67]
	v_and_b32_e32 v0, 63, v0
	v_lshlrev_b64 v[98:99], 13, v[66:67]
	v_lshl_add_u64 v[88:89], s[52:53], 0, v[10:11]
	v_lshl_add_u64 v[90:91], s[54:55], 0, v[10:11]
	v_lshl_add_u64 v[94:95], s[34:35], 0, v[64:65]
	v_lshl_add_u32 v129, v1, 8, s29
	v_lshl_or_b32 v96, v0, 3, v96
	v_lshl_add_u64 v[100:101], s[4:5], 0, v[98:99]
	v_lshl_or_b32 v98, v0, 4, v98
	s_mov_b64 s[46:47], 0
	v_lshlrev_b32_e32 v102, 2, v2
	v_lshlrev_b32_e32 v104, 2, v4
	v_lshlrev_b32_e32 v106, 2, v6
	v_lshlrev_b32_e32 v108, 2, v8
	v_readlane_b32 s49, v251, 17
	v_readlane_b32 s50, v251, 18
	v_readlane_b32 s51, v251, 19
	v_readlane_b32 s56, v251, 24
	v_readlane_b32 s57, v251, 25
	v_readlane_b32 s58, v251, 26
	v_readlane_b32 s59, v251, 27
	v_readlane_b32 s60, v251, 28
	v_readlane_b32 s61, v251, 29
	v_readlane_b32 s62, v251, 30
	v_readlane_b32 s63, v251, 31
	global_load_dwordx4 v[164:167], v[72:73], off
	global_load_dwordx4 v[170:173], v[74:75], off
	global_load_dwordx4 v[174:177], v[72:73], off offset:1024
	global_load_dwordx4 v[178:181], v[74:75], off offset:1024
	global_load_dwordx4 v[182:185], v[72:73], off offset:2048
	global_load_dwordx4 v[188:191], v[74:75], off offset:2048
	global_load_dwordx4 v[192:195], v[72:73], off offset:3072
	global_load_dwordx4 v[196:199], v[74:75], off offset:3072
	global_load_dwordx4 v[200:203], v[76:77], off
	global_load_dwordx4 v[204:207], v[78:79], off
	global_load_dwordx4 v[208:211], v[80:81], off
	global_load_dwordx4 v[212:215], v[82:83], off
	global_load_dwordx4 v[216:219], v[84:85], off
	global_load_dwordx4 v[220:223], v[86:87], off
	global_load_dwordx4 v[238:241], v[88:89], off
	global_load_dwordx4 v[242:245], v[90:91], off
	s_branch .LBB0_92

; __device__ __forceinline__ float wave_sum(float v) {
; #pragma unroll
;   for (int o = 32; o >= 1; o >>= 1) v += __shfl_xor(v, o);
;   return v;
; }
; __device__ __forceinline__ void ln_finish_row(int r, int lane, f32x4 (&x)[8], float* dstf, bf16_t* dstb, const float* g, const float* bta) {
;   float sm = 0.f;
; #pragma unroll
;   for (int k = 0; k < 8; ++k) sm += x[k][0] + x[k][1] + x[k][2] + x[k][3];
;   const float mean = wave_sum(sm) * (1.0f / 2048.0f);
;   float q = 0.f;
; #pragma unroll
;   for (int k = 0; k < 8; ++k) { x[k] = x[k] - mean; q += x[k][0] * x[k][0] + x[k][1] * x[k][1] + x[k][2] * x[k][2] + x[k][3] * x[k][3]; }
;   const float rstd = rsqrtf(wave_sum(q) * (1.0f / 2048.0f) + LN_EPS);
.LBB0_158:
	s_or_b64 exec, exec, s[48:49]
	s_waitcnt vmcnt(0)
	v_add_f32_e32 v67, v24, v25
	v_add_f32_e32 v67, v26, v67
	v_add_f32_e32 v103, v32, v33
	v_add_f32_e32 v67, v27, v67
	v_add_f32_e32 v103, v34, v103
	v_add_f32_e32 v67, 0, v67
	v_add_f32_e32 v103, v35, v103
	v_add_f32_e32 v67, v67, v103
	v_add_f32_e32 v103, v36, v37
	v_add_f32_e32 v103, v38, v103
	v_add_f32_e32 v103, v39, v103
	v_add_f32_e32 v67, v67, v103
	v_add_f32_e32 v103, v44, v45
	v_mov_b32_e32 v116, v48
	v_mov_b32_e32 v117, v52
	v_mov_b32_e32 v118, v49
	v_mov_b32_e32 v119, v53
	v_add_f32_e32 v103, v46, v103
	v_pk_add_f32 v[116:117], v[116:117], v[118:119]
	v_mov_b32_e32 v118, v50
	v_mov_b32_e32 v119, v54
	v_add_f32_e32 v103, v47, v103
	v_pk_add_f32 v[116:117], v[118:119], v[116:117]
	v_mov_b32_e32 v118, v51
	v_mov_b32_e32 v119, v55
	v_add_f32_e32 v67, v67, v103
	v_pk_add_f32 v[116:117], v[118:119], v[116:117]
	v_mov_b32_e32 v118, v57
	v_add_f32_e32 v67, v67, v116
	v_add_f32_e32 v67, v67, v117
	v_mov_b32_e32 v116, v56
	v_mov_b32_e32 v117, v60
	v_mov_b32_e32 v119, v61
	v_pk_add_f32 v[116:117], v[116:117], v[118:119]
	v_mov_b32_e32 v118, v58
	v_mov_b32_e32 v119, v62
	v_pk_add_f32 v[116:117], v[118:119], v[116:117]
	v_mov_b32_e32 v118, v59
	v_mov_b32_e32 v119, v63
	v_pk_add_f32 v[116:117], v[118:119], v[116:117]
	s_nop 1
	v_mov_b64_e32 v[130:131], v[164:165]
	v_mov_b64_e32 v[132:133], v[166:167]
	s_nop 1
	v_mov_b64_e32 v[134:135], v[170:171]
	v_mov_b64_e32 v[136:137], v[172:173]
	v_add_f32_e32 v67, v67, v116
	v_add_f32_e32 v67, v67, v117
	v_mov_b32_e32 v103, v67
	s_nop 1
	v_permlane32_swap_b32_e32 v103, v67
	s_mov_b32 s29, 0x800000
	s_waitcnt lgkmcnt(0)
	v_add_f32_e32 v67, v67, v103
	v_mov_b32_e32 v103, v67
	s_nop 1
	v_permlane16_swap_b32_e32 v103, v67
	s_waitcnt lgkmcnt(0)
	v_add_f32_e32 v67, v67, v103
	s_nop 1
	v_mov_b32_dpp v103, v67 row_ror:8 row_mask:0xf bank_mask:0xf
	s_waitcnt lgkmcnt(0)
	v_add_f32_e32 v67, v67, v103
	s_nop 1
	v_mov_b32_dpp v103, v67 row_ror:4 row_mask:0xf bank_mask:0xf
	s_waitcnt lgkmcnt(0)
	v_add_f32_e32 v67, v67, v103
	s_nop 1
	v_mov_b32_dpp v103, v67 quad_perm:[2,3,0,1] row_mask:0xf bank_mask:0xf
	s_waitcnt lgkmcnt(0)
	v_add_f32_e32 v67, v67, v103
	s_nop 1
	v_mov_b32_dpp v103, v67 quad_perm:[1,0,3,2] row_mask:0xf bank_mask:0xf
	s_waitcnt lgkmcnt(0)
	v_add_f32_e32 v67, v67, v103
	v_fmac_f32_e32 v25, 0xba000000, v67
	v_fmac_f32_e32 v33, 0xba000000, v67
	v_fmamk_f32 v123, v67, 0xba000000, v27
	v_fmamk_f32 v122, v67, 0xba000000, v26
	v_fmamk_f32 v24, v67, 0xba000000, v24
	v_mul_f32_e32 v26, v25, v25
	v_fmamk_f32 v32, v67, 0xba000000, v32
	v_mul_f32_e32 v27, v33, v33
	v_fmac_f32_e32 v26, v24, v24
	v_fmamk_f32 v120, v67, 0xba000000, v34
	v_fmac_f32_e32 v27, v32, v32
	v_fmac_f32_e32 v26, v122, v122
	v_fmamk_f32 v121, v67, 0xba000000, v35
	v_fmac_f32_e32 v27, v120, v120
	v_fmac_f32_e32 v26, v123, v123
	v_fmac_f32_e32 v27, v121, v121
	v_fmac_f32_e32 v37, 0xba000000, v67
	v_add_f32_e32 v26, v26, v27
	v_fmamk_f32 v36, v67, 0xba000000, v36
	v_mul_f32_e32 v27, v37, v37
	v_fmamk_f32 v118, v67, 0xba000000, v38
	v_fmac_f32_e32 v27, v36, v36
	v_fmamk_f32 v119, v67, 0xba000000, v39
	v_fmac_f32_e32 v27, v118, v118
	v_fmac_f32_e32 v27, v119, v119
	v_fmac_f32_e32 v45, 0xba000000, v67
	v_add_f32_e32 v26, v27, v26
	v_fmamk_f32 v44, v67, 0xba000000, v44
	v_mul_f32_e32 v27, v45, v45
	v_fmamk_f32 v116, v67, 0xba000000, v46
	v_fmac_f32_e32 v27, v44, v44
	v_fmamk_f32 v117, v67, 0xba000000, v47
	v_fmac_f32_e32 v27, v116, v116
	v_fmamk_f32 v49, v67, 0xba000000, v49
	v_fmamk_f32 v53, v67, 0xba000000, v53
	v_fmac_f32_e32 v27, v117, v117
	v_fmac_f32_e32 v48, 0xba000000, v67
	v_fmac_f32_e32 v52, 0xba000000, v67
	v_mov_b32_e32 v38, v53
	v_mov_b32_e32 v39, v49
	v_add_f32_e32 v46, v27, v26
	v_fmamk_f32 v50, v67, 0xba000000, v50
	v_fmamk_f32 v34, v67, 0xba000000, v54
	v_mov_b32_e32 v26, v52
	v_mov_b32_e32 v27, v48
	v_pk_mul_f32 v[38:39], v[38:39], v[38:39]
	v_fmamk_f32 v51, v67, 0xba000000, v51
	v_fmamk_f32 v35, v67, 0xba000000, v55
	v_pk_fma_f32 v[26:27], v[26:27], v[26:27], v[38:39]
	v_mov_b32_e32 v38, v34
	v_mov_b32_e32 v39, v50
	v_pk_fma_f32 v[26:27], v[38:39], v[38:39], v[26:27]
	v_mov_b32_e32 v38, v35
	v_mov_b32_e32 v39, v51
	v_pk_fma_f32 v[26:27], v[38:39], v[38:39], v[26:27]
	v_fmamk_f32 v57, v67, 0xba000000, v57
	v_fmamk_f32 v61, v67, 0xba000000, v61
	v_add_f32_e32 v27, v27, v46
	v_fmac_f32_e32 v56, 0xba000000, v67
	v_fmac_f32_e32 v60, 0xba000000, v67
	v_mov_b32_e32 v54, v61
	v_mov_b32_e32 v55, v57
	v_add_f32_e32 v103, v26, v27
	v_fmamk_f32 v38, v67, 0xba000000, v58
	v_fmamk_f32 v26, v67, 0xba000000, v62
	v_mov_b32_e32 v46, v60
	v_mov_b32_e32 v47, v56
	v_pk_mul_f32 v[54:55], v[54:55], v[54:55]
	v_fmamk_f32 v39, v67, 0xba000000, v59
	v_fmamk_f32 v27, v67, 0xba000000, v63
	v_pk_fma_f32 v[46:47], v[46:47], v[46:47], v[54:55]
	v_mov_b32_e32 v54, v26
	v_mov_b32_e32 v55, v38
	v_pk_fma_f32 v[46:47], v[54:55], v[54:55], v[46:47]
	v_mov_b32_e32 v54, v27
	v_mov_b32_e32 v55, v39
	v_pk_fma_f32 v[46:47], v[54:55], v[54:55], v[46:47]
	s_nop 0
	v_add_f32_e32 v47, v47, v103
	v_add_f32_e32 v46, v46, v47
	v_mov_b32_e32 v47, v46
	s_nop 1
	v_permlane32_swap_b32_e32 v47, v46
	s_waitcnt lgkmcnt(0)
	v_add_f32_e32 v46, v46, v47
	v_mov_b32_e32 v47, v46
	s_nop 1
	v_permlane16_swap_b32_e32 v47, v46
	s_waitcnt lgkmcnt(0)
	v_add_f32_e32 v46, v46, v47
	s_nop 1
	v_mov_b32_dpp v47, v46 row_ror:8 row_mask:0xf bank_mask:0xf
	s_waitcnt lgkmcnt(0)
	v_add_f32_e32 v46, v46, v47
	s_nop 1
	v_mov_b32_dpp v47, v46 row_ror:4 row_mask:0xf bank_mask:0xf
	s_waitcnt lgkmcnt(0)
	v_add_f32_e32 v46, v46, v47
	s_nop 1
	v_mov_b32_dpp v47, v46 quad_perm:[2,3,0,1] row_mask:0xf bank_mask:0xf
	s_waitcnt lgkmcnt(0)
; __device__ __forceinline__ u32x2 pack4(f32x4 v) { u32x2 r; r[0] = cvt_pk(v[0], v[1]); r[1] = cvt_pk(v[2], v[3]); return r; }
; __device__ __forceinline__ void ln_finish_row(int r, int lane, f32x4 (&x)[8], float* dstf, bf16_t* dstb, const float* g, const float* bta) {
;     ...
;   const float rstd = rsqrtf(wave_sum(q) * (1.0f / 2048.0f) + LN_EPS);
; #pragma unroll
;   for (int k = 0; k < 8; ++k) {
;     const int col = 256 * k + 4 * lane;
;     const f32x4 gg = *(const f32x4*)(g + col), bb = *(const f32x4*)(bta + col);
;     const f32x4 y = x[k] * rstd * gg + bb;
;     *(f32x4*)(dstf + (size_t)r * 2048 + col) = y;
;     if (dstb) *(u32x2*)(dstb + (size_t)r * 2048 + col) = pack4(y);
;   }
	v_add_f32_e32 v46, v46, v47
	s_nop 1
	v_mov_b32_dpp v47, v46 quad_perm:[1,0,3,2] row_mask:0xf bank_mask:0xf
	s_waitcnt lgkmcnt(0)
	v_add_f32_e32 v46, v46, v47
	v_fmamk_f32 v46, v46, 0x3a000000, v228
	v_cmp_gt_f32_e32 vcc, s29, v46
	v_mul_f32_e32 v47, 0x4b800000, v46
	s_mov_b32 s29, 0x19f09000
	v_cndmask_b32_e32 v46, v46, v47, vcc
	v_rsq_f32_e32 v46, v46
	s_nop 0
	v_mul_f32_e32 v47, 0x45800000, v46
	v_cndmask_b32_e32 v46, v46, v47, vcc
	v_pk_mul_f32 v[54:55], v[122:123], v[46:47] op_sel_hi:[1,0]
	v_pk_mul_f32 v[24:25], v[24:25], v[46:47] op_sel_hi:[1,0]
	v_pk_fma_f32 v[132:133], v[132:133], v[54:55], v[136:137]
	v_lshl_add_u64 v[54:55], s[24:25], 0, v[96:97]
	v_pk_fma_f32 v[130:131], v[130:131], v[24:25], v[134:135]
	v_add_co_u32_e32 v54, vcc, s29, v54
	v_cvt_pk_bf16_f32 v24, v130, v131
	v_cvt_pk_bf16_f32 v25, v132, v133
	v_addc_co_u32_e32 v55, vcc, 0, v55, vcc
	global_store_dwordx4 v[112:113], v[130:133], off
	global_store_dwordx2 v[54:55], v[24:25], off
	s_nop 1
	v_mov_b64_e32 v[130:131], v[174:175]
	v_mov_b64_e32 v[132:133], v[176:177]
	s_nop 0
	s_nop 1
	v_mov_b64_e32 v[134:135], v[178:179]
	v_mov_b64_e32 v[136:137], v[180:181]
	v_pk_mul_f32 v[24:25], v[120:121], v[46:47] op_sel_hi:[1,0]
	v_pk_mul_f32 v[32:33], v[32:33], v[46:47] op_sel_hi:[1,0]
	s_mov_b32 s29, 0x109000
	v_pk_mul_f32 v[36:37], v[36:37], v[46:47] op_sel_hi:[1,0]
	v_pk_mul_f32 v[26:27], v[26:27], v[46:47] op_sel_hi:[1,0]
	v_pk_fma_f32 v[120:121], v[130:131], v[32:33], v[134:135]
	v_pk_fma_f32 v[122:123], v[132:133], v[24:25], v[136:137]
	v_add_co_u32_e32 v24, vcc, s29, v110
	v_cvt_pk_bf16_f32 v32, v120, v121
	s_nop 0
	v_addc_co_u32_e32 v25, vcc, 0, v111, vcc
	v_cvt_pk_bf16_f32 v33, v122, v123
	global_store_dwordx4 v[24:25], v[120:123], off offset:1024
	global_store_dwordx2 v[54:55], v[32:33], off offset:512
	s_nop 1
	v_mov_b64_e32 v[120:121], v[182:183]
	v_mov_b64_e32 v[122:123], v[184:185]
	s_nop 0
	s_nop 1
	v_mov_b64_e32 v[130:131], v[188:189]
	v_mov_b64_e32 v[132:133], v[190:191]
	v_pk_mul_f32 v[32:33], v[118:119], v[46:47] op_sel_hi:[1,0]
	s_mov_b32 s29, 0x10a000
	v_pk_fma_f32 v[118:119], v[120:121], v[36:37], v[130:131]
	v_pk_fma_f32 v[120:121], v[122:123], v[32:33], v[132:133]
	v_cvt_pk_bf16_f32 v32, v118, v119
	v_cvt_pk_bf16_f32 v33, v120, v121
	global_store_dwordx4 v[24:25], v[118:121], off offset:2048
	global_store_dwordx2 v[54:55], v[32:33], off offset:1024
	s_nop 1
	v_mov_b64_e32 v[118:119], v[192:193]
	v_mov_b64_e32 v[120:121], v[194:195]
	s_nop 0
	s_nop 1
	v_mov_b64_e32 v[130:131], v[196:197]
	v_mov_b64_e32 v[132:133], v[198:199]
	v_pk_mul_f32 v[32:33], v[116:117], v[46:47] op_sel_hi:[1,0]
	v_pk_mul_f32 v[36:37], v[44:45], v[46:47] op_sel_hi:[1,0]
	v_add_co_u32_e32 v44, vcc, s29, v110
	v_pk_fma_f32 v[116:117], v[118:119], v[36:37], v[130:131]
	v_pk_fma_f32 v[118:119], v[120:121], v[32:33], v[132:133]
	global_store_dwordx4 v[24:25], v[116:119], off offset:3072
	v_cvt_pk_bf16_f32 v24, v116, v117
	v_cvt_pk_bf16_f32 v25, v118, v119
	global_store_dwordx2 v[54:55], v[24:25], off offset:1536
	s_nop 1
	v_mov_b64_e32 v[116:117], v[200:201]
	v_mov_b64_e32 v[118:119], v[202:203]
	s_nop 1
	v_mov_b64_e32 v[120:121], v[204:205]
	v_mov_b64_e32 v[122:123], v[206:207]
	v_pk_mul_f32 v[24:25], v[50:51], v[46:47] op_sel_hi:[1,0]
	v_pk_mul_f32 v[32:33], v[48:49], v[46:47] op_sel_hi:[1,0]
	v_addc_co_u32_e32 v45, vcc, 0, v111, vcc
	v_pk_mul_f32 v[36:37], v[56:57], v[46:47] op_sel_hi:[1,0]
	v_pk_fma_f32 v[48:49], v[116:117], v[32:33], v[120:121]
	v_pk_fma_f32 v[50:51], v[118:119], v[24:25], v[122:123]
	v_cvt_pk_bf16_f32 v24, v48, v49
	v_cvt_pk_bf16_f32 v25, v50, v51
	global_store_dwordx4 v[44:45], v[48:51], off
	global_store_dwordx2 v[54:55], v[24:25], off offset:2048
	s_nop 1
	v_mov_b64_e32 v[48:49], v[208:209]
	v_mov_b64_e32 v[50:51], v[210:211]
	s_nop 0
	s_nop 1
	v_mov_b64_e32 v[110:111], v[212:213]
	v_mov_b64_e32 v[112:113], v[214:215]
	v_pk_mul_f32 v[24:25], v[34:35], v[46:47] op_sel_hi:[1,0]
	v_pk_mul_f32 v[32:33], v[52:53], v[46:47] op_sel_hi:[1,0]
	v_pk_fma_f32 v[34:35], v[50:51], v[24:25], v[112:113]
	v_pk_fma_f32 v[32:33], v[48:49], v[32:33], v[110:111]
	v_cvt_pk_bf16_f32 v25, v34, v35
	v_cvt_pk_bf16_f32 v24, v32, v33
	global_store_dwordx4 v[44:45], v[32:35], off offset:1024
	global_store_dwordx2 v[54:55], v[24:25], off offset:2560
	s_nop 1
	v_mov_b64_e32 v[32:33], v[216:217]
	v_mov_b64_e32 v[34:35], v[218:219]
	s_nop 0
	s_nop 1
	v_mov_b64_e32 v[48:49], v[220:221]
	v_mov_b64_e32 v[50:51], v[222:223]
	v_pk_mul_f32 v[24:25], v[38:39], v[46:47] op_sel_hi:[1,0]
	v_pk_fma_f32 v[32:33], v[32:33], v[36:37], v[48:49]
	v_pk_fma_f32 v[34:35], v[34:35], v[24:25], v[50:51]
	v_cvt_pk_bf16_f32 v24, v32, v33
	v_cvt_pk_bf16_f32 v25, v34, v35
	global_store_dwordx4 v[44:45], v[32:35], off offset:2048
	global_store_dwordx2 v[54:55], v[24:25], off offset:3072
	s_nop 1
	v_mov_b64_e32 v[32:33], v[238:239]
	v_mov_b64_e32 v[34:35], v[240:241]
	s_nop 0
	s_nop 1
	v_mov_b64_e32 v[36:37], v[242:243]
	v_mov_b64_e32 v[38:39], v[244:245]
	v_pk_mul_f32 v[24:25], v[60:61], v[46:47] op_sel_hi:[1,0]
	v_pk_fma_f32 v[26:27], v[26:27], v[34:35], v[38:39]
	v_pk_fma_f32 v[24:25], v[24:25], v[32:33], v[36:37]
	global_store_dwordx4 v[44:45], v[24:27], off offset:3072
	s_nop 1
	v_cvt_pk_bf16_f32 v24, v24, v25
	v_cvt_pk_bf16_f32 v25, v26, v27
	global_store_dwordx2 v[54:55], v[24:25], off offset:3584
	s_and_saveexec_b64 s[38:39], s[36:37]
	s_cbranch_execz .LBB0_91
; __device__ __forceinline__ float wave_sum(float v) {
; #pragma unroll
;   for (int o = 32; o >= 1; o >>= 1) v += __shfl_xor(v, o);
;   return v;
; }
; __device__ __forceinline__ void ln_finish_row(int r, int lane, f32x4 (&x)[8], float* dstf, bf16_t* dstb, const float* g, const float* bta) {
;   float sm = 0.f;
; #pragma unroll
;   for (int k = 0; k < 8; ++k) sm += x[k][0] + x[k][1] + x[k][2] + x[k][3];
;   const float mean = wave_sum(sm) * (1.0f / 2048.0f);
;   float q = 0.f;
; #pragma unroll
;   for (int k = 0; k < 8; ++k) { x[k] = x[k] - mean; q += x[k][0] * x[k][0] + x[k][1] * x[k][1] + x[k][2] * x[k][2] + x[k][3] * x[k][3]; }
;   const float rstd = rsqrtf(wave_sum(q) * (1.0f / 2048.0f) + LN_EPS);
	v_add_f32_e32 v24, v0, v1
	v_add_f32_e32 v24, v2, v24
	v_add_f32_e32 v25, v4, v5
	v_add_f32_e32 v24, v3, v24
	v_add_f32_e32 v25, v6, v25
	v_add_f32_e32 v24, 0, v24
	v_add_f32_e32 v25, v7, v25
	v_add_f32_e32 v24, v25, v24
	v_add_f32_e32 v25, v8, v9
	v_add_f32_e32 v25, v10, v25
	v_add_f32_e32 v25, v11, v25
	v_add_f32_e32 v24, v25, v24
	v_add_f32_e32 v25, v12, v13
	v_add_f32_e32 v25, v14, v25
	v_add_f32_e32 v25, v15, v25
	v_add_f32_e32 v32, v25, v24
	v_mov_b32_e32 v24, v20
	v_mov_b32_e32 v25, v16
	v_mov_b32_e32 v26, v21
	v_mov_b32_e32 v27, v17
	v_pk_add_f32 v[24:25], v[24:25], v[26:27]
	v_mov_b32_e32 v26, v22
	v_mov_b32_e32 v27, v18
	v_pk_add_f32 v[24:25], v[26:27], v[24:25]
	v_mov_b32_e32 v26, v23
	v_mov_b32_e32 v27, v19
	v_pk_add_f32 v[24:25], v[26:27], v[24:25]
	v_mov_b32_e32 v26, v41
	v_add_f32_e32 v25, v25, v32
	v_add_f32_e32 v32, v24, v25
	v_mov_b32_e32 v24, v40
	v_mov_b32_e32 v25, v28
	v_mov_b32_e32 v27, v29
	v_pk_add_f32 v[24:25], v[24:25], v[26:27]
	v_mov_b32_e32 v26, v42
	v_mov_b32_e32 v27, v30
	v_pk_add_f32 v[24:25], v[26:27], v[24:25]
	v_mov_b32_e32 v26, v43
	v_mov_b32_e32 v27, v31
	v_pk_add_f32 v[24:25], v[26:27], v[24:25]
	s_mov_b32 s29, 0x800000
	v_add_f32_e32 v25, v25, v32
	v_add_f32_e32 v24, v24, v25
	v_mov_b32_e32 v25, v24
	s_nop 1
	v_permlane32_swap_b32_e32 v25, v24
	v_readlane_b32 s34, v254, 30
	v_readlane_b32 s35, v254, 31
	v_mov_b32_e32 v103, v65
	v_mov_b32_e32 v105, v65
	s_waitcnt lgkmcnt(0)
	v_add_f32_e32 v24, v24, v25
	v_mov_b32_e32 v25, v24
	s_nop 1
	v_permlane16_swap_b32_e32 v25, v24
	v_mov_b32_e32 v107, v65
	v_mov_b32_e32 v109, v65
	s_waitcnt lgkmcnt(0)
	v_add_f32_e32 v24, v24, v25
	s_nop 1
	v_mov_b32_dpp v25, v24 row_ror:8 row_mask:0xf bank_mask:0xf
	s_waitcnt lgkmcnt(0)
	v_add_f32_e32 v24, v24, v25
	s_nop 1
	v_mov_b32_dpp v25, v24 row_ror:4 row_mask:0xf bank_mask:0xf
	s_waitcnt lgkmcnt(0)
	v_add_f32_e32 v24, v24, v25
	s_nop 1
	v_mov_b32_dpp v25, v24 quad_perm:[2,3,0,1] row_mask:0xf bank_mask:0xf
	s_waitcnt lgkmcnt(0)
	v_add_f32_e32 v24, v24, v25
	s_nop 1
	v_mov_b32_dpp v25, v24 quad_perm:[1,0,3,2] row_mask:0xf bank_mask:0xf
	s_waitcnt lgkmcnt(0)
	v_add_f32_e32 v44, v24, v25
	v_fmamk_f32 v1, v44, 0xba000000, v1
	v_fmamk_f32 v5, v44, 0xba000000, v5
	v_fmac_f32_e32 v0, 0xba000000, v44
	v_mul_f32_e32 v24, v1, v1
	v_fmac_f32_e32 v4, 0xba000000, v44
	v_mul_f32_e32 v25, v5, v5
	v_fmamk_f32 v2, v44, 0xba000000, v2
	v_fmac_f32_e32 v24, v0, v0
	v_fmamk_f32 v6, v44, 0xba000000, v6
	v_fmac_f32_e32 v25, v4, v4
	v_fmamk_f32 v3, v44, 0xba000000, v3
	v_fmac_f32_e32 v24, v2, v2
	v_fmamk_f32 v7, v44, 0xba000000, v7
	v_fmac_f32_e32 v25, v6, v6
	v_fmac_f32_e32 v24, v3, v3
	v_fmac_f32_e32 v25, v7, v7
	v_fmamk_f32 v9, v44, 0xba000000, v9
	v_add_f32_e32 v24, v24, v25
	v_fmac_f32_e32 v8, 0xba000000, v44
	v_mul_f32_e32 v25, v9, v9
	v_fmamk_f32 v10, v44, 0xba000000, v10
	v_fmac_f32_e32 v25, v8, v8
	v_fmamk_f32 v11, v44, 0xba000000, v11
	v_fmac_f32_e32 v25, v10, v10
	v_fmac_f32_e32 v25, v11, v11
	v_fmamk_f32 v13, v44, 0xba000000, v13
	v_add_f32_e32 v24, v25, v24
	v_fmac_f32_e32 v12, 0xba000000, v44
	v_mul_f32_e32 v25, v13, v13
	v_fmamk_f32 v14, v44, 0xba000000, v14
	v_fmac_f32_e32 v25, v12, v12
	v_fmamk_f32 v15, v44, 0xba000000, v15
	v_fmac_f32_e32 v25, v14, v14
	v_fmamk_f32 v17, v44, 0xba000000, v17
	v_fmamk_f32 v21, v44, 0xba000000, v21
	v_fmac_f32_e32 v25, v15, v15
	v_fmac_f32_e32 v16, 0xba000000, v44
	v_fmac_f32_e32 v20, 0xba000000, v44
	v_mov_b32_e32 v26, v21
	v_mov_b32_e32 v27, v17
	v_add_f32_e32 v45, v25, v24
	v_mov_b32_e32 v24, v20
	v_mov_b32_e32 v25, v16
	v_pk_mul_f32 v[26:27], v[26:27], v[26:27]
	v_fmamk_f32 v18, v44, 0xba000000, v18
	v_pk_fma_f32 v[36:37], v[24:25], v[24:25], v[26:27]
	s_nop 1
	v_mov_b64_e32 v[24:25], v[164:165]
	v_mov_b64_e32 v[26:27], v[166:167]
	s_nop 1
	v_mov_b64_e32 v[32:33], v[170:171]
	v_mov_b64_e32 v[34:35], v[172:173]
	v_fmamk_f32 v22, v44, 0xba000000, v22
	v_fmamk_f32 v19, v44, 0xba000000, v19
	v_fmamk_f32 v23, v44, 0xba000000, v23
	v_mov_b32_e32 v38, v22
	v_mov_b32_e32 v39, v18
	v_pk_fma_f32 v[36:37], v[38:39], v[38:39], v[36:37]
	v_mov_b32_e32 v38, v23
	v_mov_b32_e32 v39, v19
	v_pk_fma_f32 v[36:37], v[38:39], v[38:39], v[36:37]
	v_fmamk_f32 v29, v44, 0xba000000, v29
	v_fmamk_f32 v41, v44, 0xba000000, v41
	v_add_f32_e32 v37, v37, v45
	v_fmac_f32_e32 v28, 0xba000000, v44
	v_fmac_f32_e32 v40, 0xba000000, v44
	v_mov_b32_e32 v38, v41
	v_mov_b32_e32 v39, v29
	v_add_f32_e32 v45, v36, v37
	v_fmamk_f32 v30, v44, 0xba000000, v30
	v_fmamk_f32 v42, v44, 0xba000000, v42
	v_mov_b32_e32 v36, v40
	v_mov_b32_e32 v37, v28
	v_pk_mul_f32 v[38:39], v[38:39], v[38:39]
	v_fmamk_f32 v31, v44, 0xba000000, v31
	v_fmamk_f32 v43, v44, 0xba000000, v43
	v_pk_fma_f32 v[36:37], v[36:37], v[36:37], v[38:39]
	v_mov_b32_e32 v38, v42
	v_mov_b32_e32 v39, v30
	v_pk_fma_f32 v[36:37], v[38:39], v[38:39], v[36:37]
	v_mov_b32_e32 v38, v43
	v_mov_b32_e32 v39, v31
	v_pk_fma_f32 v[36:37], v[38:39], v[38:39], v[36:37]
	v_lshlrev_b64 v[38:39], 13, v[114:115]
	v_add_f32_e32 v37, v37, v45
	v_add_f32_e32 v36, v36, v37
	v_mov_b32_e32 v37, v36
	s_nop 1
	v_permlane32_swap_b32_e32 v37, v36
	v_lshl_add_u64 v[38:39], s[34:35], 0, v[38:39]
	s_waitcnt lgkmcnt(0)
	v_add_f32_e32 v36, v36, v37
	v_mov_b32_e32 v37, v36
	s_nop 1
	v_permlane16_swap_b32_e32 v37, v36
	s_waitcnt lgkmcnt(0)
	v_add_f32_e32 v36, v36, v37
	s_nop 1
	v_mov_b32_dpp v37, v36 row_ror:8 row_mask:0xf bank_mask:0xf
	s_waitcnt lgkmcnt(0)
; __device__ __forceinline__ u32x2 pack4(f32x4 v) { u32x2 r; r[0] = cvt_pk(v[0], v[1]); r[1] = cvt_pk(v[2], v[3]); return r; }
; __device__ __forceinline__ void ln_finish_row(int r, int lane, f32x4 (&x)[8], float* dstf, bf16_t* dstb, const float* g, const float* bta) {
;     ...
;   const float rstd = rsqrtf(wave_sum(q) * (1.0f / 2048.0f) + LN_EPS);
; #pragma unroll
;   for (int k = 0; k < 8; ++k) {
;     const int col = 256 * k + 4 * lane;
;     const f32x4 gg = *(const f32x4*)(g + col), bb = *(const f32x4*)(bta + col);
;     const f32x4 y = x[k] * rstd * gg + bb;
;     *(f32x4*)(dstf + (size_t)r * 2048 + col) = y;
;     if (dstb) *(u32x2*)(dstb + (size_t)r * 2048 + col) = pack4(y);
;   }
	v_add_f32_e32 v36, v36, v37
	s_nop 1
	v_mov_b32_dpp v37, v36 row_ror:4 row_mask:0xf bank_mask:0xf
	s_waitcnt lgkmcnt(0)
	v_add_f32_e32 v36, v36, v37
	s_nop 1
	v_mov_b32_dpp v37, v36 quad_perm:[2,3,0,1] row_mask:0xf bank_mask:0xf
	s_waitcnt lgkmcnt(0)
	v_add_f32_e32 v36, v36, v37
	s_nop 1
	v_mov_b32_dpp v37, v36 quad_perm:[1,0,3,2] row_mask:0xf bank_mask:0xf
	s_waitcnt lgkmcnt(0)
	v_add_f32_e32 v36, v36, v37
	v_fmamk_f32 v36, v36, 0x3a000000, v228
	v_mul_f32_e32 v37, 0x4b800000, v36
	v_cmp_gt_f32_e32 vcc, s29, v36
	s_nop 1
	v_cndmask_b32_e32 v36, v36, v37, vcc
	v_rsq_f32_e32 v36, v36
	s_nop 0
	v_mul_f32_e32 v37, 0x45800000, v36
	v_cndmask_b32_e32 v36, v36, v37, vcc
	v_pk_mul_f32 v[44:45], v[0:1], v[36:37] op_sel_hi:[1,0]
	v_pk_mul_f32 v[46:47], v[2:3], v[36:37] op_sel_hi:[1,0]
	v_pk_fma_f32 v[24:25], v[24:25], v[44:45], v[32:33]
	v_pk_fma_f32 v[26:27], v[26:27], v[46:47], v[34:35]
	v_lshl_add_u64 v[44:45], v[38:39], 0, v[64:65]
	global_store_dwordx4 v[44:45], v[24:27], off
	v_pk_mul_f32 v[48:49], v[6:7], v[36:37] op_sel_hi:[1,0]
	v_pk_mul_f32 v[50:51], v[4:5], v[36:37] op_sel_hi:[1,0]
	v_cvt_pk_bf16_f32 v24, v24, v25
	v_cvt_pk_bf16_f32 v25, v26, v27
	v_lshlrev_b64 v[26:27], 12, v[114:115]
	v_lshl_add_u64 v[46:47], v[94:95], 0, v[26:27]
	global_store_dwordx2 v[46:47], v[24:25], off
	s_nop 1
	v_mov_b64_e32 v[24:25], v[174:175]
	v_mov_b64_e32 v[26:27], v[176:177]
	s_nop 0
	s_nop 1
	v_mov_b64_e32 v[32:33], v[178:179]
	v_mov_b64_e32 v[34:35], v[180:181]
	v_pk_fma_f32 v[24:25], v[24:25], v[50:51], v[32:33]
	v_pk_fma_f32 v[26:27], v[26:27], v[48:49], v[34:35]
	global_store_dwordx4 v[44:45], v[24:27], off offset:1024
	v_pk_mul_f32 v[48:49], v[10:11], v[36:37] op_sel_hi:[1,0]
	v_pk_mul_f32 v[50:51], v[8:9], v[36:37] op_sel_hi:[1,0]
	v_cvt_pk_bf16_f32 v24, v24, v25
	v_cvt_pk_bf16_f32 v25, v26, v27
	global_store_dwordx2 v[46:47], v[24:25], off offset:512
	s_nop 1
	v_mov_b64_e32 v[24:25], v[182:183]
	v_mov_b64_e32 v[26:27], v[184:185]
	s_nop 0
	s_nop 1
	v_mov_b64_e32 v[32:33], v[188:189]
	v_mov_b64_e32 v[34:35], v[190:191]
	v_pk_fma_f32 v[24:25], v[24:25], v[50:51], v[32:33]
	v_pk_fma_f32 v[26:27], v[26:27], v[48:49], v[34:35]
	global_store_dwordx4 v[44:45], v[24:27], off offset:2048
	v_pk_mul_f32 v[48:49], v[14:15], v[36:37] op_sel_hi:[1,0]
	v_pk_mul_f32 v[50:51], v[12:13], v[36:37] op_sel_hi:[1,0]
	v_cvt_pk_bf16_f32 v24, v24, v25
	v_cvt_pk_bf16_f32 v25, v26, v27
	global_store_dwordx2 v[46:47], v[24:25], off offset:1024
	s_nop 1
	v_mov_b64_e32 v[24:25], v[192:193]
	v_mov_b64_e32 v[26:27], v[194:195]
	s_nop 0
	s_nop 1
	v_mov_b64_e32 v[32:33], v[196:197]
	v_mov_b64_e32 v[34:35], v[198:199]
	v_pk_fma_f32 v[24:25], v[24:25], v[50:51], v[32:33]
	v_pk_fma_f32 v[26:27], v[26:27], v[48:49], v[34:35]
	global_store_dwordx4 v[44:45], v[24:27], off offset:3072
	v_pk_mul_f32 v[48:49], v[18:19], v[36:37] op_sel_hi:[1,0]
	v_pk_mul_f32 v[50:51], v[16:17], v[36:37] op_sel_hi:[1,0]
	v_cvt_pk_bf16_f32 v24, v24, v25
	v_cvt_pk_bf16_f32 v25, v26, v27
	global_store_dwordx2 v[46:47], v[24:25], off offset:1536
	s_nop 1
	v_mov_b64_e32 v[24:25], v[200:201]
	v_mov_b64_e32 v[26:27], v[202:203]
	s_nop 0
	s_nop 1
	v_mov_b64_e32 v[32:33], v[204:205]
	v_mov_b64_e32 v[34:35], v[206:207]
	v_lshl_add_u64 v[44:45], v[38:39], 0, v[102:103]
	v_pk_fma_f32 v[24:25], v[24:25], v[50:51], v[32:33]
	v_pk_fma_f32 v[26:27], v[26:27], v[48:49], v[34:35]
	global_store_dwordx4 v[44:45], v[24:27], off
	v_pk_mul_f32 v[48:49], v[22:23], v[36:37] op_sel_hi:[1,0]
	v_pk_mul_f32 v[50:51], v[20:21], v[36:37] op_sel_hi:[1,0]
	v_cvt_pk_bf16_f32 v24, v24, v25
	v_cvt_pk_bf16_f32 v25, v26, v27
	global_store_dwordx2 v[46:47], v[24:25], off offset:2048
	s_nop 1
	v_mov_b64_e32 v[24:25], v[208:209]
	v_mov_b64_e32 v[26:27], v[210:211]
	s_nop 0
	s_nop 1
	v_mov_b64_e32 v[32:33], v[212:213]
	v_mov_b64_e32 v[34:35], v[214:215]
	v_lshl_add_u64 v[44:45], v[38:39], 0, v[104:105]
	v_pk_fma_f32 v[24:25], v[24:25], v[50:51], v[32:33]
	v_pk_fma_f32 v[26:27], v[26:27], v[48:49], v[34:35]
	global_store_dwordx4 v[44:45], v[24:27], off
	v_pk_mul_f32 v[48:49], v[30:31], v[36:37] op_sel_hi:[1,0]
	v_pk_mul_f32 v[50:51], v[28:29], v[36:37] op_sel_hi:[1,0]
	v_cvt_pk_bf16_f32 v24, v24, v25
	v_cvt_pk_bf16_f32 v25, v26, v27
	global_store_dwordx2 v[46:47], v[24:25], off offset:2560
	s_nop 1
	v_mov_b64_e32 v[24:25], v[216:217]
	v_mov_b64_e32 v[26:27], v[218:219]
	s_nop 0
	s_nop 1
	v_mov_b64_e32 v[32:33], v[220:221]
	v_mov_b64_e32 v[34:35], v[222:223]
	v_lshl_add_u64 v[44:45], v[38:39], 0, v[106:107]
	v_lshl_add_u64 v[38:39], v[38:39], 0, v[108:109]
	v_pk_fma_f32 v[24:25], v[24:25], v[50:51], v[32:33]
	v_pk_fma_f32 v[26:27], v[26:27], v[48:49], v[34:35]
	global_store_dwordx4 v[44:45], v[24:27], off
	v_pk_mul_f32 v[44:45], v[42:43], v[36:37] op_sel_hi:[1,0]
	v_pk_mul_f32 v[36:37], v[40:41], v[36:37] op_sel_hi:[1,0]
	v_cvt_pk_bf16_f32 v24, v24, v25
	v_cvt_pk_bf16_f32 v25, v26, v27
	global_store_dwordx2 v[46:47], v[24:25], off offset:3072
	s_nop 1
	v_mov_b64_e32 v[24:25], v[238:239]
	v_mov_b64_e32 v[26:27], v[240:241]
	s_nop 0
	s_nop 1
	v_mov_b64_e32 v[32:33], v[242:243]
	v_mov_b64_e32 v[34:35], v[244:245]
	v_pk_fma_f32 v[24:25], v[36:37], v[24:25], v[32:33]
	v_pk_fma_f32 v[26:27], v[44:45], v[26:27], v[34:35]
	global_store_dwordx4 v[38:39], v[24:27], off
	s_nop 1
	v_cvt_pk_bf16_f32 v24, v24, v25
	v_cvt_pk_bf16_f32 v25, v26, v27
	global_store_dwordx2 v[46:47], v[24:25], off offset:3584
	s_branch .LBB0_91

; __device__ __forceinline__ void ln_finish_row(int r, int lane, f32x4 (&x)[8], float* dstf, bf16_t* dstb, const float* g, const float* bta) {
;     ...
;   for (int k = 0; k < 8; ++k) {
;     const int col = 256 * k + 4 * lane;
;     const f32x4 gg = *(const f32x4*)(g + col), bb = *(const f32x4*)(bta + col);
; __device__ __forceinline__ void phase_ln(const Params& p, const float* src, float* dstf, bf16_t* dstb, const float* g, const float* bta, int which) {
;   int tid = threadIdx.x; asm volatile("" : "+v"(tid));
;   const int w = tid >> 6, lane = tid & 63;
;   const int nw = gridDim.x * 8;
;   for (int r = blockIdx.x * 8 + w; r < NTOK; r += 2 * nw) {
;     const int r2 = r + nw;
.LBB0_1491:
	v_readlane_b32 s74, v255, 33
	s_andn2_b64 vcc, exec, s[30:31]
	v_readlane_b32 s72, v255, 32
	v_readlane_b32 s75, v255, 34
	s_cbranch_vccnz .LBB0_1564
	v_mov_b32_e32 v0, v226
	v_readlane_b32 s29, v252, 44
	v_ashrrev_i32_e32 v1, 6, v0
	s_nop 0
	v_add_u32_e32 v66, s29, v1
	s_movk_i32 s29, 0x2400
	v_cmp_gt_i32_e32 vcc, s29, v66
	s_and_saveexec_b64 s[38:39], vcc
	s_cbranch_execz .LBB0_1563
	v_and_b32_e32 v3, 64, v230
	v_add_u32_e32 v3, 64, v3
	v_xor_b32_e32 v4, 32, v230
	v_cmp_lt_i32_e32 vcc, v4, v3
	v_lshlrev_b32_e32 v2, 2, v0
	v_and_b32_e32 v2, 0xfc, v2
	v_cndmask_b32_e32 v4, v230, v4, vcc
	v_lshlrev_b32_e32 v120, 2, v4
	v_xor_b32_e32 v4, 16, v230
	v_cmp_lt_i32_e32 vcc, v4, v3
	v_readlane_b32 s40, v251, 16
	v_readlane_b32 s54, v251, 30
	v_cndmask_b32_e32 v4, v230, v4, vcc
	v_lshlrev_b32_e32 v121, 2, v4
	v_xor_b32_e32 v4, 8, v230
	v_cmp_lt_i32_e32 vcc, v4, v3
	v_readlane_b32 s55, v251, 31
	v_mov_b32_e32 v7, v65
	v_cndmask_b32_e32 v4, v230, v4, vcc
	v_lshlrev_b32_e32 v122, 2, v4
	v_xor_b32_e32 v4, 4, v230
	v_cmp_lt_i32_e32 vcc, v4, v3
	v_mov_b32_e32 v9, v65
	v_readlane_b32 s34, v252, 57
	v_cndmask_b32_e32 v4, v230, v4, vcc
	v_lshlrev_b32_e32 v123, 2, v4
	v_xor_b32_e32 v4, 2, v230
	v_cmp_lt_i32_e32 vcc, v4, v3
	v_lshlrev_b32_e32 v64, 2, v2
	v_readlane_b32 s35, v252, 58
	v_cndmask_b32_e32 v4, v230, v4, vcc
	v_lshlrev_b32_e32 v124, 2, v4
	v_xor_b32_e32 v4, 1, v230
	v_cmp_lt_i32_e32 vcc, v4, v3
	v_mov_b32_e32 v11, v65
	v_lshl_add_u64 v[68:69], s[34:35], 0, v[64:65]
	v_cndmask_b32_e32 v3, v230, v4, vcc
	v_or_b32_e32 v4, 0x400, v2
	v_lshlrev_b32_e32 v6, 2, v4
	v_lshl_add_u64 v[74:75], s[54:55], 0, v[6:7]
	v_lshl_add_u64 v[76:77], s[20:21], 0, v[6:7]
	v_or_b32_e32 v6, 0x500, v2
	v_lshlrev_b32_e32 v8, 2, v6
	v_lshl_add_u64 v[78:79], s[54:55], 0, v[8:9]
	v_lshl_add_u64 v[80:81], s[20:21], 0, v[8:9]
	v_or_b32_e32 v8, 0x600, v2
	v_lshlrev_b32_e32 v10, 2, v8
	v_lshl_add_u64 v[82:83], s[54:55], 0, v[10:11]
	v_lshl_add_u64 v[84:85], s[20:21], 0, v[10:11]
	v_or_b32_e32 v10, 0x700, v2
	v_readlane_b32 s34, v254, 30
	v_readlane_b32 s29, v255, 8
	v_and_b32_e32 v0, 63, v0
	v_ashrrev_i32_e32 v67, 31, v66
	v_readlane_b32 s41, v251, 17
	v_lshlrev_b32_e32 v12, 2, v10
	v_mov_b32_e32 v13, v65
	v_readlane_b32 s35, v254, 31
	v_lshl_add_u32 v126, v1, 8, s29
	v_lshlrev_b32_e32 v94, 4, v0
	v_lshlrev_b64 v[0:1], 13, v[66:67]
	v_lshlrev_b32_e32 v125, 2, v3
	v_lshl_add_u64 v[70:71], s[54:55], 0, v[64:65]
	v_lshl_add_u64 v[72:73], s[20:21], 0, v[64:65]
	v_lshl_add_u64 v[86:87], s[54:55], 0, v[12:13]
	v_lshl_add_u64 v[88:89], s[20:21], 0, v[12:13]
	v_lshl_add_u64 v[90:91], s[34:35], 0, v[64:65]
	v_lshl_add_u64 v[92:93], s[74:75], 0, v[64:65]
	v_mov_b32_e32 v95, v65
	v_lshl_add_u64 v[96:97], s[24:25], 0, v[0:1]
	v_lshl_add_u64 v[98:99], s[22:23], 0, v[0:1]
	s_mov_b64 s[40:41], 0
	v_lshlrev_b32_e32 v100, 2, v2
	v_lshlrev_b32_e32 v102, 2, v4
	v_lshlrev_b32_e32 v104, 2, v6
	v_lshlrev_b32_e32 v106, 2, v8
	v_lshlrev_b32_e32 v108, 2, v10
	v_readlane_b32 s42, v251, 18
	v_readlane_b32 s43, v251, 19
	v_readlane_b32 s44, v251, 20
	v_readlane_b32 s45, v251, 21
	v_readlane_b32 s46, v251, 22
	v_readlane_b32 s47, v251, 23
	v_readlane_b32 s48, v251, 24
	v_readlane_b32 s49, v251, 25
	v_readlane_b32 s50, v251, 26
	v_readlane_b32 s51, v251, 27
	v_readlane_b32 s52, v251, 28
	v_readlane_b32 s53, v251, 29
	global_load_dwordx4 v[160:163], v[70:71], off
	global_load_dwordx4 v[164:167], v[72:73], off
	global_load_dwordx4 v[170:173], v[70:71], off offset:1024
	global_load_dwordx4 v[174:177], v[72:73], off offset:1024
	global_load_dwordx4 v[178:181], v[70:71], off offset:2048
	global_load_dwordx4 v[182:185], v[72:73], off offset:2048
	global_load_dwordx4 v[188:191], v[70:71], off offset:3072
	global_load_dwordx4 v[192:195], v[72:73], off offset:3072
	global_load_dwordx4 v[196:199], v[74:75], off
	global_load_dwordx4 v[200:203], v[76:77], off
	global_load_dwordx4 v[204:207], v[78:79], off
	global_load_dwordx4 v[208:211], v[80:81], off
	global_load_dwordx4 v[212:215], v[82:83], off
	global_load_dwordx4 v[216:219], v[84:85], off
	global_load_dwordx4 v[220:223], v[86:87], off
	global_load_dwordx4 v[238:241], v[88:89], off
	s_branch .LBB0_1495

; __device__ __forceinline__ float wave_sum(float v) {
; #pragma unroll
;   for (int o = 32; o >= 1; o >>= 1) v += __shfl_xor(v, o);
;   return v;
; }
; __device__ __forceinline__ void ln_finish_row(int r, int lane, f32x4 (&x)[8], float* dstf, bf16_t* dstb, const float* g, const float* bta) {
;   float sm = 0.f;
; #pragma unroll
;   for (int k = 0; k < 8; ++k) sm += x[k][0] + x[k][1] + x[k][2] + x[k][3];
;   const float mean = wave_sum(sm) * (1.0f / 2048.0f);
;   float q = 0.f;
; #pragma unroll
;   for (int k = 0; k < 8; ++k) { x[k] = x[k] - mean; q += x[k][0] * x[k][0] + x[k][1] * x[k][1] + x[k][2] * x[k][2] + x[k][3] * x[k][3]; }
;   const float rstd = rsqrtf(wave_sum(q) * (1.0f / 2048.0f) + LN_EPS);
.LBB0_1561:
	s_or_b64 exec, exec, s[42:43]
	s_waitcnt vmcnt(0)
	v_add_f32_e32 v64, v20, v21
	v_add_f32_e32 v64, v22, v64
	v_add_f32_e32 v67, v28, v29
	v_add_f32_e32 v64, v23, v64
	v_add_f32_e32 v67, v30, v67
	v_add_f32_e32 v64, 0, v64
	v_add_f32_e32 v67, v31, v67
	v_add_f32_e32 v64, v64, v67
	v_add_f32_e32 v67, v36, v37
	v_add_f32_e32 v67, v38, v67
	v_add_f32_e32 v67, v39, v67
	v_add_f32_e32 v64, v64, v67
	v_add_f32_e32 v67, v44, v45
	v_mov_b32_e32 v112, v48
	v_mov_b32_e32 v113, v52
	v_mov_b32_e32 v114, v49
	v_mov_b32_e32 v115, v53
	v_add_f32_e32 v67, v46, v67
	v_pk_add_f32 v[112:113], v[112:113], v[114:115]
	v_mov_b32_e32 v114, v50
	v_mov_b32_e32 v115, v54
	v_add_f32_e32 v67, v47, v67
	v_pk_add_f32 v[112:113], v[114:115], v[112:113]
	v_mov_b32_e32 v114, v51
	v_mov_b32_e32 v115, v55
	v_add_f32_e32 v64, v64, v67
	v_pk_add_f32 v[112:113], v[114:115], v[112:113]
	v_mov_b32_e32 v114, v57
	v_add_f32_e32 v64, v64, v112
	v_add_f32_e32 v64, v64, v113
	v_mov_b32_e32 v112, v56
	v_mov_b32_e32 v113, v60
	v_mov_b32_e32 v115, v61
	v_pk_add_f32 v[112:113], v[112:113], v[114:115]
	v_mov_b32_e32 v114, v58
	v_mov_b32_e32 v115, v62
	v_pk_add_f32 v[112:113], v[114:115], v[112:113]
	v_mov_b32_e32 v114, v59
	v_mov_b32_e32 v115, v63
	v_pk_add_f32 v[112:113], v[114:115], v[112:113]
	s_nop 1
	v_mov_b64_e32 v[128:129], v[160:161]
	v_mov_b64_e32 v[130:131], v[162:163]
	s_nop 1
	v_mov_b64_e32 v[132:133], v[164:165]
	v_mov_b64_e32 v[134:135], v[166:167]
	v_add_f32_e32 v64, v64, v112
	v_add_f32_e32 v64, v64, v113
	v_mov_b32_e32 v67, v64
	s_nop 1
	v_permlane32_swap_b32_e32 v67, v64
	s_mov_b32 s29, 0x800000
	s_waitcnt lgkmcnt(0)
	v_add_f32_e32 v64, v64, v67
	v_mov_b32_e32 v67, v64
	s_nop 1
	v_permlane16_swap_b32_e32 v67, v64
	s_waitcnt lgkmcnt(0)
	v_add_f32_e32 v64, v64, v67
	s_nop 1
	v_mov_b32_dpp v67, v64 row_ror:8 row_mask:0xf bank_mask:0xf
	s_waitcnt lgkmcnt(0)
	v_add_f32_e32 v64, v64, v67
	s_nop 1
	v_mov_b32_dpp v67, v64 row_ror:4 row_mask:0xf bank_mask:0xf
	s_waitcnt lgkmcnt(0)
	v_add_f32_e32 v64, v64, v67
	s_nop 1
	v_mov_b32_dpp v67, v64 quad_perm:[2,3,0,1] row_mask:0xf bank_mask:0xf
	s_waitcnt lgkmcnt(0)
	v_add_f32_e32 v64, v64, v67
	s_nop 1
	v_mov_b32_dpp v67, v64 quad_perm:[1,0,3,2] row_mask:0xf bank_mask:0xf
	s_waitcnt lgkmcnt(0)
	v_add_f32_e32 v64, v64, v67
	v_fmac_f32_e32 v21, 0xba000000, v64
	v_fmac_f32_e32 v29, 0xba000000, v64
	v_fmamk_f32 v119, v64, 0xba000000, v23
	v_fmamk_f32 v118, v64, 0xba000000, v22
	v_fmamk_f32 v20, v64, 0xba000000, v20
	v_mul_f32_e32 v22, v21, v21
	v_fmamk_f32 v28, v64, 0xba000000, v28
	v_mul_f32_e32 v23, v29, v29
	v_fmac_f32_e32 v22, v20, v20
	v_fmamk_f32 v116, v64, 0xba000000, v30
	v_fmac_f32_e32 v23, v28, v28
	v_fmac_f32_e32 v22, v118, v118
	v_fmamk_f32 v117, v64, 0xba000000, v31
	v_fmac_f32_e32 v23, v116, v116
	v_fmac_f32_e32 v22, v119, v119
	v_fmac_f32_e32 v23, v117, v117
	v_fmac_f32_e32 v37, 0xba000000, v64
	v_add_f32_e32 v22, v22, v23
	v_fmamk_f32 v36, v64, 0xba000000, v36
	v_mul_f32_e32 v23, v37, v37
	v_fmamk_f32 v114, v64, 0xba000000, v38
	v_fmac_f32_e32 v23, v36, v36
	v_fmamk_f32 v115, v64, 0xba000000, v39
	v_fmac_f32_e32 v23, v114, v114
	v_fmac_f32_e32 v23, v115, v115
	v_fmac_f32_e32 v45, 0xba000000, v64
	v_add_f32_e32 v22, v23, v22
	v_fmamk_f32 v44, v64, 0xba000000, v44
	v_mul_f32_e32 v23, v45, v45
	v_fmamk_f32 v112, v64, 0xba000000, v46
	v_fmac_f32_e32 v23, v44, v44
	v_fmamk_f32 v113, v64, 0xba000000, v47
	v_fmac_f32_e32 v23, v112, v112
	v_fmamk_f32 v49, v64, 0xba000000, v49
	v_fmamk_f32 v53, v64, 0xba000000, v53
	v_fmac_f32_e32 v23, v113, v113
	v_fmac_f32_e32 v48, 0xba000000, v64
	v_fmac_f32_e32 v52, 0xba000000, v64
	v_mov_b32_e32 v38, v53
	v_mov_b32_e32 v39, v49
	v_add_f32_e32 v46, v23, v22
	v_fmamk_f32 v50, v64, 0xba000000, v50
	v_fmamk_f32 v30, v64, 0xba000000, v54
	v_mov_b32_e32 v22, v52
	v_mov_b32_e32 v23, v48
	v_pk_mul_f32 v[38:39], v[38:39], v[38:39]
	v_fmamk_f32 v51, v64, 0xba000000, v51
	v_fmamk_f32 v31, v64, 0xba000000, v55
	v_pk_fma_f32 v[22:23], v[22:23], v[22:23], v[38:39]
	v_mov_b32_e32 v38, v30
	v_mov_b32_e32 v39, v50
	v_pk_fma_f32 v[22:23], v[38:39], v[38:39], v[22:23]
	v_mov_b32_e32 v38, v31
	v_mov_b32_e32 v39, v51
	v_pk_fma_f32 v[22:23], v[38:39], v[38:39], v[22:23]
	v_fmamk_f32 v57, v64, 0xba000000, v57
	v_fmamk_f32 v61, v64, 0xba000000, v61
	v_add_f32_e32 v23, v23, v46
	v_fmac_f32_e32 v56, 0xba000000, v64
	v_fmac_f32_e32 v60, 0xba000000, v64
	v_mov_b32_e32 v54, v61
	v_mov_b32_e32 v55, v57
	v_add_f32_e32 v67, v22, v23
	v_fmamk_f32 v38, v64, 0xba000000, v58
	v_fmamk_f32 v22, v64, 0xba000000, v62
	v_mov_b32_e32 v46, v60
	v_mov_b32_e32 v47, v56
	v_pk_mul_f32 v[54:55], v[54:55], v[54:55]
	v_fmamk_f32 v39, v64, 0xba000000, v59
	v_fmamk_f32 v23, v64, 0xba000000, v63
	v_pk_fma_f32 v[46:47], v[46:47], v[46:47], v[54:55]
	v_mov_b32_e32 v54, v22
	v_mov_b32_e32 v55, v38
	v_pk_fma_f32 v[46:47], v[54:55], v[54:55], v[46:47]
	v_mov_b32_e32 v54, v23
	v_mov_b32_e32 v55, v39
	v_pk_fma_f32 v[46:47], v[54:55], v[54:55], v[46:47]
	s_nop 0
	v_add_f32_e32 v47, v47, v67
	v_add_f32_e32 v46, v46, v47
	v_mov_b32_e32 v47, v46
	s_nop 1
	v_permlane32_swap_b32_e32 v47, v46
	s_waitcnt lgkmcnt(0)
	v_add_f32_e32 v46, v46, v47
	v_mov_b32_e32 v47, v46
	s_nop 1
	v_permlane16_swap_b32_e32 v47, v46
	s_waitcnt lgkmcnt(0)
	v_add_f32_e32 v46, v46, v47
	s_nop 1
	v_mov_b32_dpp v47, v46 row_ror:8 row_mask:0xf bank_mask:0xf
	s_waitcnt lgkmcnt(0)
	v_add_f32_e32 v46, v46, v47
	s_nop 1
	v_mov_b32_dpp v47, v46 row_ror:4 row_mask:0xf bank_mask:0xf
	s_waitcnt lgkmcnt(0)
	v_add_f32_e32 v46, v46, v47
	s_nop 1
	v_mov_b32_dpp v47, v46 quad_perm:[2,3,0,1] row_mask:0xf bank_mask:0xf
	s_waitcnt lgkmcnt(0)
; __device__ __forceinline__ u32x2 pack4(f32x4 v) { u32x2 r; r[0] = cvt_pk(v[0], v[1]); r[1] = cvt_pk(v[2], v[3]); return r; }
; __device__ __forceinline__ void ln_finish_row(int r, int lane, f32x4 (&x)[8], float* dstf, bf16_t* dstb, const float* g, const float* bta) {
;   float sm = 0.f;
; #pragma unroll
;   for (int k = 0; k < 8; ++k) sm += x[k][0] + x[k][1] + x[k][2] + x[k][3];
;   const float mean = wave_sum(sm) * (1.0f / 2048.0f);
;     ...
;   const float rstd = rsqrtf(wave_sum(q) * (1.0f / 2048.0f) + LN_EPS);
; #pragma unroll
;   for (int k = 0; k < 8; ++k) {
;     const int col = 256 * k + 4 * lane;
;     const f32x4 gg = *(const f32x4*)(g + col), bb = *(const f32x4*)(bta + col);
;     const f32x4 y = x[k] * rstd * gg + bb;
;     *(f32x4*)(dstf + (size_t)r * 2048 + col) = y;
;     if (dstb) *(u32x2*)(dstb + (size_t)r * 2048 + col) = pack4(y);
;   }
	v_add_f32_e32 v46, v46, v47
	s_nop 1
	v_mov_b32_dpp v47, v46 quad_perm:[1,0,3,2] row_mask:0xf bank_mask:0xf
	s_waitcnt lgkmcnt(0)
	v_add_f32_e32 v46, v46, v47
	v_fmamk_f32 v46, v46, 0x3a000000, v228
	v_cmp_gt_f32_e32 vcc, s29, v46
	v_mul_f32_e32 v47, 0x4b800000, v46
	s_movk_i32 s29, 0x1000
	v_cndmask_b32_e32 v46, v46, v47, vcc
	v_rsq_f32_e32 v46, v46
	s_nop 0
	v_mul_f32_e32 v47, 0x45800000, v46
	v_cndmask_b32_e32 v46, v46, v47, vcc
	v_pk_mul_f32 v[20:21], v[20:21], v[46:47] op_sel_hi:[1,0]
	v_pk_mul_f32 v[54:55], v[118:119], v[46:47] op_sel_hi:[1,0]
	v_pk_fma_f32 v[128:129], v[128:129], v[20:21], v[132:133]
	v_pk_fma_f32 v[130:131], v[130:131], v[54:55], v[134:135]
	v_lshl_add_u64 v[20:21], v[98:99], 0, v[94:95]
	global_store_dwordx4 v[20:21], v[128:131], off
	s_nop 1
	v_mov_b64_e32 v[128:129], v[170:171]
	v_mov_b64_e32 v[130:131], v[172:173]
	s_nop 0
	s_nop 1
	v_mov_b64_e32 v[132:133], v[174:175]
	v_mov_b64_e32 v[134:135], v[176:177]
	v_pk_mul_f32 v[54:55], v[116:117], v[46:47] op_sel_hi:[1,0]
	v_pk_mul_f32 v[28:29], v[28:29], v[46:47] op_sel_hi:[1,0]
	v_pk_mul_f32 v[36:37], v[36:37], v[46:47] op_sel_hi:[1,0]
	v_pk_mul_f32 v[22:23], v[22:23], v[46:47] op_sel_hi:[1,0]
	v_pk_fma_f32 v[116:117], v[128:129], v[28:29], v[132:133]
	v_pk_fma_f32 v[118:119], v[130:131], v[54:55], v[134:135]
	global_store_dwordx4 v[20:21], v[116:119], off offset:1024
	s_nop 1
	v_mov_b64_e32 v[116:117], v[178:179]
	v_mov_b64_e32 v[118:119], v[180:181]
	s_nop 0
	s_nop 1
	v_mov_b64_e32 v[128:129], v[182:183]
	v_mov_b64_e32 v[130:131], v[184:185]
	v_pk_mul_f32 v[28:29], v[114:115], v[46:47] op_sel_hi:[1,0]
	v_pk_fma_f32 v[114:115], v[116:117], v[36:37], v[128:129]
	v_pk_fma_f32 v[116:117], v[118:119], v[28:29], v[130:131]
	global_store_dwordx4 v[20:21], v[114:117], off offset:2048
	s_nop 1
	v_mov_b64_e32 v[114:115], v[188:189]
	v_mov_b64_e32 v[116:117], v[190:191]
	s_nop 0
	s_nop 1
	v_mov_b64_e32 v[128:129], v[192:193]
	v_mov_b64_e32 v[130:131], v[194:195]
	v_pk_mul_f32 v[28:29], v[112:113], v[46:47] op_sel_hi:[1,0]
	v_pk_mul_f32 v[36:37], v[44:45], v[46:47] op_sel_hi:[1,0]
	v_add_co_u32_e32 v44, vcc, s29, v20
	v_pk_fma_f32 v[112:113], v[114:115], v[36:37], v[128:129]
	v_pk_fma_f32 v[114:115], v[116:117], v[28:29], v[130:131]
	global_store_dwordx4 v[20:21], v[112:115], off offset:3072
	s_nop 1
	v_mov_b64_e32 v[112:113], v[196:197]
	v_mov_b64_e32 v[114:115], v[198:199]
	s_nop 0
	s_nop 1
	v_mov_b64_e32 v[116:117], v[200:201]
	v_mov_b64_e32 v[118:119], v[202:203]
	v_pk_mul_f32 v[28:29], v[50:51], v[46:47] op_sel_hi:[1,0]
	v_pk_mul_f32 v[36:37], v[48:49], v[46:47] op_sel_hi:[1,0]
	v_addc_co_u32_e32 v45, vcc, 0, v21, vcc
	v_pk_mul_f32 v[20:21], v[30:31], v[46:47] op_sel_hi:[1,0]
	v_pk_fma_f32 v[48:49], v[112:113], v[36:37], v[116:117]
	v_pk_fma_f32 v[50:51], v[114:115], v[28:29], v[118:119]
	global_store_dwordx4 v[44:45], v[48:51], off
	s_nop 1
	v_mov_b64_e32 v[48:49], v[204:205]
	v_mov_b64_e32 v[50:51], v[206:207]
	s_nop 0
	s_nop 1
	v_mov_b64_e32 v[112:113], v[208:209]
	v_mov_b64_e32 v[114:115], v[210:211]
	v_pk_mul_f32 v[28:29], v[52:53], v[46:47] op_sel_hi:[1,0]
	v_pk_mul_f32 v[36:37], v[56:57], v[46:47] op_sel_hi:[1,0]
	v_pk_fma_f32 v[28:29], v[48:49], v[28:29], v[112:113]
	v_pk_fma_f32 v[30:31], v[50:51], v[20:21], v[114:115]
	global_store_dwordx4 v[44:45], v[28:31], off offset:1024
	s_nop 1
	v_mov_b64_e32 v[28:29], v[212:213]
	v_mov_b64_e32 v[30:31], v[214:215]
	s_nop 0
	s_nop 1
	v_mov_b64_e32 v[48:49], v[216:217]
	v_mov_b64_e32 v[50:51], v[218:219]
	v_pk_mul_f32 v[20:21], v[38:39], v[46:47] op_sel_hi:[1,0]
	v_pk_fma_f32 v[28:29], v[28:29], v[36:37], v[48:49]
	v_pk_fma_f32 v[30:31], v[30:31], v[20:21], v[50:51]
	global_store_dwordx4 v[44:45], v[28:31], off offset:2048
	s_nop 1
	v_mov_b64_e32 v[28:29], v[220:221]
	v_mov_b64_e32 v[30:31], v[222:223]
	s_nop 0
	s_nop 1
	v_mov_b64_e32 v[36:37], v[238:239]
	v_mov_b64_e32 v[38:39], v[240:241]
	v_pk_mul_f32 v[20:21], v[60:61], v[46:47] op_sel_hi:[1,0]
	v_pk_fma_f32 v[22:23], v[30:31], v[22:23], v[38:39]
	v_pk_fma_f32 v[20:21], v[28:29], v[20:21], v[36:37]
	global_store_dwordx4 v[44:45], v[20:23], off offset:3072
	s_and_saveexec_b64 s[42:43], s[36:37]
	s_cbranch_execz .LBB0_1494
	v_add_f32_e32 v20, v0, v1
	v_add_f32_e32 v20, v2, v20
	v_add_f32_e32 v21, v4, v5
	v_add_f32_e32 v20, v3, v20
	v_add_f32_e32 v21, v6, v21
	v_add_f32_e32 v20, 0, v20
	v_add_f32_e32 v21, v7, v21
	v_add_f32_e32 v20, v21, v20
	v_add_f32_e32 v21, v8, v9
	v_add_f32_e32 v21, v10, v21
	v_add_f32_e32 v21, v11, v21
	v_add_f32_e32 v20, v21, v20
	v_add_f32_e32 v21, v12, v13
	v_add_f32_e32 v21, v14, v21
	v_add_f32_e32 v21, v15, v21
	v_add_f32_e32 v28, v21, v20
	v_mov_b32_e32 v20, v24
	v_mov_b32_e32 v21, v16
	v_mov_b32_e32 v22, v25
	v_mov_b32_e32 v23, v17
	v_pk_add_f32 v[20:21], v[20:21], v[22:23]
	v_mov_b32_e32 v22, v26
	v_mov_b32_e32 v23, v18
	v_pk_add_f32 v[20:21], v[22:23], v[20:21]
	v_mov_b32_e32 v22, v27
	v_mov_b32_e32 v23, v19
	v_pk_add_f32 v[20:21], v[22:23], v[20:21]
	v_mov_b32_e32 v22, v41
	v_add_f32_e32 v21, v21, v28
	v_add_f32_e32 v28, v20, v21
	v_mov_b32_e32 v20, v40
	v_mov_b32_e32 v21, v32
	v_mov_b32_e32 v23, v33
	v_pk_add_f32 v[20:21], v[20:21], v[22:23]
	v_mov_b32_e32 v22, v42
	v_mov_b32_e32 v23, v34
	v_pk_add_f32 v[20:21], v[22:23], v[20:21]
	v_mov_b32_e32 v22, v43
	v_mov_b32_e32 v23, v35
	v_pk_add_f32 v[20:21], v[22:23], v[20:21]
	s_mov_b32 s29, 0x800000
	v_add_f32_e32 v21, v21, v28
	v_add_f32_e32 v20, v20, v21
	v_mov_b32_e32 v21, v20
	s_nop 1
	v_permlane32_swap_b32_e32 v21, v20
	v_ashrrev_i32_e32 v111, 31, v110
	v_mov_b32_e32 v101, v65
	v_mov_b32_e32 v103, v65
	v_mov_b32_e32 v105, v65
	s_waitcnt lgkmcnt(0)
; __device__ __forceinline__ void ln_finish_row(int r, int lane, f32x4 (&x)[8], float* dstf, bf16_t* dstb, const float* g, const float* bta) {
;   float sm = 0.f;
; #pragma unroll
;   for (int k = 0; k < 8; ++k) sm += x[k][0] + x[k][1] + x[k][2] + x[k][3];
;   const float mean = wave_sum(sm) * (1.0f / 2048.0f);
;   float q = 0.f;
; #pragma unroll
;   for (int k = 0; k < 8; ++k) { x[k] = x[k] - mean; q += x[k][0] * x[k][0] + x[k][1] * x[k][1] + x[k][2] * x[k][2] + x[k][3] * x[k][3]; }
;   const float rstd = rsqrtf(wave_sum(q) * (1.0f / 2048.0f) + LN_EPS);
	v_add_f32_e32 v20, v20, v21
	v_mov_b32_e32 v21, v20
	s_nop 1
	v_permlane16_swap_b32_e32 v21, v20
	v_mov_b32_e32 v107, v65
	v_mov_b32_e32 v109, v65
	s_waitcnt lgkmcnt(0)
	v_add_f32_e32 v20, v20, v21
	s_nop 1
	v_mov_b32_dpp v21, v20 row_ror:8 row_mask:0xf bank_mask:0xf
	s_waitcnt lgkmcnt(0)
	v_add_f32_e32 v20, v20, v21
	s_nop 1
	v_mov_b32_dpp v21, v20 row_ror:4 row_mask:0xf bank_mask:0xf
	s_waitcnt lgkmcnt(0)
	v_add_f32_e32 v20, v20, v21
	s_nop 1
	v_mov_b32_dpp v21, v20 quad_perm:[2,3,0,1] row_mask:0xf bank_mask:0xf
	s_waitcnt lgkmcnt(0)
	v_add_f32_e32 v20, v20, v21
	s_nop 1
	v_mov_b32_dpp v21, v20 quad_perm:[1,0,3,2] row_mask:0xf bank_mask:0xf
	s_waitcnt lgkmcnt(0)
	v_add_f32_e32 v44, v20, v21
	v_fmamk_f32 v1, v44, 0xba000000, v1
	v_fmamk_f32 v5, v44, 0xba000000, v5
	v_fmac_f32_e32 v0, 0xba000000, v44
	v_mul_f32_e32 v20, v1, v1
	v_fmac_f32_e32 v4, 0xba000000, v44
	v_mul_f32_e32 v21, v5, v5
	v_fmamk_f32 v2, v44, 0xba000000, v2
	v_fmac_f32_e32 v20, v0, v0
	v_fmamk_f32 v6, v44, 0xba000000, v6
	v_fmac_f32_e32 v21, v4, v4
	v_fmamk_f32 v3, v44, 0xba000000, v3
	v_fmac_f32_e32 v20, v2, v2
	v_fmamk_f32 v7, v44, 0xba000000, v7
	v_fmac_f32_e32 v21, v6, v6
	v_fmac_f32_e32 v20, v3, v3
	v_fmac_f32_e32 v21, v7, v7
	v_fmamk_f32 v9, v44, 0xba000000, v9
	v_add_f32_e32 v20, v20, v21
	v_fmac_f32_e32 v8, 0xba000000, v44
	v_mul_f32_e32 v21, v9, v9
	v_fmamk_f32 v10, v44, 0xba000000, v10
	v_fmac_f32_e32 v21, v8, v8
	v_fmamk_f32 v11, v44, 0xba000000, v11
	v_fmac_f32_e32 v21, v10, v10
	v_fmac_f32_e32 v21, v11, v11
	v_fmamk_f32 v13, v44, 0xba000000, v13
	v_add_f32_e32 v20, v21, v20
	v_fmac_f32_e32 v12, 0xba000000, v44
	v_mul_f32_e32 v21, v13, v13
	v_fmamk_f32 v14, v44, 0xba000000, v14
	v_fmac_f32_e32 v21, v12, v12
	v_fmamk_f32 v15, v44, 0xba000000, v15
	v_fmac_f32_e32 v21, v14, v14
	v_fmamk_f32 v17, v44, 0xba000000, v17
	v_fmamk_f32 v25, v44, 0xba000000, v25
	v_fmac_f32_e32 v21, v15, v15
	v_fmac_f32_e32 v16, 0xba000000, v44
	v_fmac_f32_e32 v24, 0xba000000, v44
	v_mov_b32_e32 v22, v25
	v_mov_b32_e32 v23, v17
	v_add_f32_e32 v45, v21, v20
	v_mov_b32_e32 v20, v24
	v_mov_b32_e32 v21, v16
	v_pk_mul_f32 v[22:23], v[22:23], v[22:23]
	v_fmamk_f32 v18, v44, 0xba000000, v18
	v_pk_fma_f32 v[36:37], v[20:21], v[20:21], v[22:23]
	s_nop 1
	v_mov_b64_e32 v[20:21], v[160:161]
	v_mov_b64_e32 v[22:23], v[162:163]
	s_nop 1
	v_mov_b64_e32 v[28:29], v[164:165]
	v_mov_b64_e32 v[30:31], v[166:167]
	v_fmamk_f32 v26, v44, 0xba000000, v26
	v_fmamk_f32 v19, v44, 0xba000000, v19
	v_fmamk_f32 v27, v44, 0xba000000, v27
	v_mov_b32_e32 v38, v26
	v_mov_b32_e32 v39, v18
	v_pk_fma_f32 v[36:37], v[38:39], v[38:39], v[36:37]
	v_mov_b32_e32 v38, v27
	v_mov_b32_e32 v39, v19
	v_pk_fma_f32 v[36:37], v[38:39], v[38:39], v[36:37]
	v_fmamk_f32 v33, v44, 0xba000000, v33
	v_fmamk_f32 v41, v44, 0xba000000, v41
	v_add_f32_e32 v37, v37, v45
	v_fmac_f32_e32 v32, 0xba000000, v44
	v_fmac_f32_e32 v40, 0xba000000, v44
	v_mov_b32_e32 v38, v41
	v_mov_b32_e32 v39, v33
	v_add_f32_e32 v45, v36, v37
	v_fmamk_f32 v34, v44, 0xba000000, v34
	v_fmamk_f32 v42, v44, 0xba000000, v42
	v_mov_b32_e32 v36, v40
	v_mov_b32_e32 v37, v32
	v_pk_mul_f32 v[38:39], v[38:39], v[38:39]
	v_fmamk_f32 v35, v44, 0xba000000, v35
	v_fmamk_f32 v43, v44, 0xba000000, v43
	v_pk_fma_f32 v[36:37], v[36:37], v[36:37], v[38:39]
	v_mov_b32_e32 v38, v42
	v_mov_b32_e32 v39, v34
	v_pk_fma_f32 v[36:37], v[38:39], v[38:39], v[36:37]
	v_mov_b32_e32 v38, v43
	v_mov_b32_e32 v39, v35
	v_pk_fma_f32 v[36:37], v[38:39], v[38:39], v[36:37]
	v_lshlrev_b64 v[38:39], 13, v[110:111]
	v_add_f32_e32 v37, v37, v45
	v_add_f32_e32 v36, v36, v37
	v_mov_b32_e32 v37, v36
	s_nop 1
	v_permlane32_swap_b32_e32 v37, v36
	v_lshl_add_u64 v[38:39], s[22:23], 0, v[38:39]
	s_waitcnt lgkmcnt(0)
	v_add_f32_e32 v36, v36, v37
	v_mov_b32_e32 v37, v36
	s_nop 1
	v_permlane16_swap_b32_e32 v37, v36
	s_waitcnt lgkmcnt(0)
	v_add_f32_e32 v36, v36, v37
	s_nop 1
	v_mov_b32_dpp v37, v36 row_ror:8 row_mask:0xf bank_mask:0xf
	s_waitcnt lgkmcnt(0)
	v_add_f32_e32 v36, v36, v37
	s_nop 1
	v_mov_b32_dpp v37, v36 row_ror:4 row_mask:0xf bank_mask:0xf
	s_waitcnt lgkmcnt(0)
	v_add_f32_e32 v36, v36, v37
	s_nop 1
	v_mov_b32_dpp v37, v36 quad_perm:[2,3,0,1] row_mask:0xf bank_mask:0xf
	s_waitcnt lgkmcnt(0)
; __device__ __forceinline__ u32x2 pack4(f32x4 v) { u32x2 r; r[0] = cvt_pk(v[0], v[1]); r[1] = cvt_pk(v[2], v[3]); return r; }
; __device__ __forceinline__ void ln_finish_row(int r, int lane, f32x4 (&x)[8], float* dstf, bf16_t* dstb, const float* g, const float* bta) {
;     ...
;   const float rstd = rsqrtf(wave_sum(q) * (1.0f / 2048.0f) + LN_EPS);
; #pragma unroll
;   for (int k = 0; k < 8; ++k) {
;     const int col = 256 * k + 4 * lane;
;     const f32x4 gg = *(const f32x4*)(g + col), bb = *(const f32x4*)(bta + col);
;     const f32x4 y = x[k] * rstd * gg + bb;
;     *(f32x4*)(dstf + (size_t)r * 2048 + col) = y;
;     if (dstb) *(u32x2*)(dstb + (size_t)r * 2048 + col) = pack4(y);
;   }
	v_add_f32_e32 v36, v36, v37
	s_nop 1
	v_mov_b32_dpp v37, v36 quad_perm:[1,0,3,2] row_mask:0xf bank_mask:0xf
	s_waitcnt lgkmcnt(0)
	v_add_f32_e32 v36, v36, v37
	v_fmamk_f32 v36, v36, 0x3a000000, v228
	v_mul_f32_e32 v37, 0x4b800000, v36
	v_cmp_gt_f32_e32 vcc, s29, v36
	s_nop 1
	v_cndmask_b32_e32 v36, v36, v37, vcc
	v_rsq_f32_e32 v36, v36
	s_nop 0
	v_mul_f32_e32 v37, 0x45800000, v36
	v_cndmask_b32_e32 v36, v36, v37, vcc
	v_pk_mul_f32 v[44:45], v[0:1], v[36:37] op_sel_hi:[1,0]
	v_pk_mul_f32 v[46:47], v[2:3], v[36:37] op_sel_hi:[1,0]
	v_pk_fma_f32 v[20:21], v[20:21], v[44:45], v[28:29]
	v_pk_fma_f32 v[22:23], v[22:23], v[46:47], v[30:31]
	v_lshl_add_u64 v[44:45], v[38:39], 0, v[100:101]
	global_store_dwordx4 v[44:45], v[20:23], off
	s_nop 1
	v_mov_b64_e32 v[20:21], v[170:171]
	v_mov_b64_e32 v[22:23], v[172:173]
	s_nop 0
	s_nop 1
	v_mov_b64_e32 v[28:29], v[174:175]
	v_mov_b64_e32 v[30:31], v[176:177]
	v_pk_mul_f32 v[46:47], v[6:7], v[36:37] op_sel_hi:[1,0]
	v_pk_mul_f32 v[48:49], v[4:5], v[36:37] op_sel_hi:[1,0]
	v_pk_fma_f32 v[22:23], v[22:23], v[46:47], v[30:31]
	v_pk_fma_f32 v[20:21], v[20:21], v[48:49], v[28:29]
	global_store_dwordx4 v[44:45], v[20:23], off offset:1024
	s_nop 1
	v_mov_b64_e32 v[20:21], v[178:179]
	v_mov_b64_e32 v[22:23], v[180:181]
	s_nop 0
	s_nop 1
	v_mov_b64_e32 v[28:29], v[182:183]
	v_mov_b64_e32 v[30:31], v[184:185]
	v_pk_mul_f32 v[46:47], v[10:11], v[36:37] op_sel_hi:[1,0]
	v_pk_mul_f32 v[48:49], v[8:9], v[36:37] op_sel_hi:[1,0]
	v_pk_fma_f32 v[22:23], v[22:23], v[46:47], v[30:31]
	v_pk_fma_f32 v[20:21], v[20:21], v[48:49], v[28:29]
	global_store_dwordx4 v[44:45], v[20:23], off offset:2048
	s_nop 1
	v_mov_b64_e32 v[20:21], v[188:189]
	v_mov_b64_e32 v[22:23], v[190:191]
	s_nop 0
	s_nop 1
	v_mov_b64_e32 v[28:29], v[192:193]
	v_mov_b64_e32 v[30:31], v[194:195]
	v_pk_mul_f32 v[46:47], v[14:15], v[36:37] op_sel_hi:[1,0]
	v_pk_mul_f32 v[48:49], v[12:13], v[36:37] op_sel_hi:[1,0]
	v_pk_fma_f32 v[22:23], v[22:23], v[46:47], v[30:31]
	v_pk_fma_f32 v[20:21], v[20:21], v[48:49], v[28:29]
	global_store_dwordx4 v[44:45], v[20:23], off offset:3072
	s_nop 1
	v_mov_b64_e32 v[20:21], v[196:197]
	v_mov_b64_e32 v[22:23], v[198:199]
	s_nop 0
	s_nop 1
	v_mov_b64_e32 v[28:29], v[200:201]
	v_mov_b64_e32 v[30:31], v[202:203]
	v_pk_mul_f32 v[46:47], v[18:19], v[36:37] op_sel_hi:[1,0]
	v_pk_mul_f32 v[48:49], v[16:17], v[36:37] op_sel_hi:[1,0]
	v_lshl_add_u64 v[44:45], v[38:39], 0, v[102:103]
	v_pk_fma_f32 v[20:21], v[20:21], v[48:49], v[28:29]
	v_pk_fma_f32 v[22:23], v[22:23], v[46:47], v[30:31]
	global_store_dwordx4 v[44:45], v[20:23], off
	s_nop 1
	v_mov_b64_e32 v[20:21], v[204:205]
	v_mov_b64_e32 v[22:23], v[206:207]
	s_nop 0
	s_nop 1
	v_mov_b64_e32 v[28:29], v[208:209]
	v_mov_b64_e32 v[30:31], v[210:211]
	v_pk_mul_f32 v[46:47], v[26:27], v[36:37] op_sel_hi:[1,0]
	v_pk_mul_f32 v[48:49], v[24:25], v[36:37] op_sel_hi:[1,0]
	v_lshl_add_u64 v[44:45], v[38:39], 0, v[104:105]
	v_pk_fma_f32 v[20:21], v[20:21], v[48:49], v[28:29]
	v_pk_fma_f32 v[22:23], v[22:23], v[46:47], v[30:31]
	global_store_dwordx4 v[44:45], v[20:23], off
	s_nop 1
	v_mov_b64_e32 v[20:21], v[212:213]
	v_mov_b64_e32 v[22:23], v[214:215]
	s_nop 0
	s_nop 1
	v_mov_b64_e32 v[28:29], v[216:217]
	v_mov_b64_e32 v[30:31], v[218:219]
	v_pk_mul_f32 v[46:47], v[34:35], v[36:37] op_sel_hi:[1,0]
	v_pk_mul_f32 v[48:49], v[32:33], v[36:37] op_sel_hi:[1,0]
	v_lshl_add_u64 v[44:45], v[38:39], 0, v[106:107]
	v_pk_fma_f32 v[20:21], v[20:21], v[48:49], v[28:29]
	v_pk_fma_f32 v[22:23], v[22:23], v[46:47], v[30:31]
	global_store_dwordx4 v[44:45], v[20:23], off
	s_nop 1
	v_mov_b64_e32 v[20:21], v[220:221]
	v_mov_b64_e32 v[22:23], v[222:223]
	s_nop 0
	s_nop 1
	v_mov_b64_e32 v[28:29], v[238:239]
	v_mov_b64_e32 v[30:31], v[240:241]
	v_pk_mul_f32 v[44:45], v[42:43], v[36:37] op_sel_hi:[1,0]
	v_pk_mul_f32 v[36:37], v[40:41], v[36:37] op_sel_hi:[1,0]
	v_pk_fma_f32 v[22:23], v[22:23], v[44:45], v[30:31]
	v_pk_fma_f32 v[20:21], v[20:21], v[36:37], v[28:29]
	v_lshl_add_u64 v[28:29], v[38:39], 0, v[108:109]
	global_store_dwordx4 v[28:29], v[20:23], off
	s_branch .LBB0_1494
